# grid barriers: releasing leader also bumps eight per-XCC copies of the generation word; local waiters poll their own XCC's copy (poll traffic spread over eight lines)
# speedup vs baseline: 1.0107x; 1.0107x over previous
; __device__ __forceinline__ unsigned xb_ld(unsigned* p)              { return __hip_atomic_load(p, __ATOMIC_RELAXED, __HIP_MEMORY_SCOPE_AGENT); }
; #define XB_SPIN(cond, bar) do { unsigned _sp = 0; while (cond) { __builtin_amdgcn_s_sleep(1); \
;     if ((++_sp & 255u) == 0u) { if (xb_ld(&(bar)[XB_TMO])) break; if (_sp > XB_SPIN_CAP) { atomicAdd(&(bar)[XB_TMO], 1u); break; } } } } while (0)
; __device__ __forceinline__ void xcd_barrier(const XcdBarrier& b) {
;     ...
;         } else {
;             XB_SPIN(xb_ld(&bar[XB_XGEN(b.x)]) == gen, bar);
;             __builtin_amdgcn_fence(__ATOMIC_ACQUIRE, "agent");
;             asm volatile("s_waitcnt vmcnt(0)" ::: "memory");
;         }
.LBB0_88:
	s_or_b64 exec, exec, s[8:9]
	v_cvt_f32_u32_e32 v4, v2
	s_waitcnt vmcnt(0)
	v_readfirstlane_b32 s6, v3
	v_sub_u32_e32 v3, 0, v2
	v_rcp_iflag_f32_e32 v4, v4
	v_add_u32_e32 v5, s6, v1
	v_mul_f32_e32 v4, 0x4f7ffffe, v4
	v_cvt_u32_f32_e32 v4, v4
	v_mul_lo_u32 v1, v3, v4
	v_mul_hi_u32 v1, v4, v1
	v_add_u32_e32 v1, v4, v1
	v_mul_hi_u32 v1, v5, v1
	v_mul_lo_u32 v3, v1, v2
	v_sub_u32_e32 v3, v5, v3
	v_add_u32_e32 v4, 1, v1
	v_cmp_ge_u32_e32 vcc, v3, v2
	s_nop 1
	v_cndmask_b32_e32 v1, v1, v4, vcc
	v_sub_u32_e32 v4, v3, v2
	v_cndmask_b32_e32 v3, v3, v4, vcc
	v_add_u32_e32 v4, 1, v1
	v_cmp_ge_u32_e32 vcc, v3, v2
	v_add_u32_e32 v3, 1, v5
	s_nop 0
	v_cndmask_b32_e32 v1, v1, v4, vcc
	v_mul_lo_u32 v4, v2, v1
	v_add_u32_e32 v2, v4, v2
	v_cmp_ne_u32_e32 vcc, v3, v2
	s_and_saveexec_b64 s[6:7], vcc
	s_xor_b64 s[6:7], exec, s[6:7]
	s_cbranch_execz .LBB0_102
	s_waitcnt lgkmcnt(0)
	s_add_u32 s12, s96, 0x183500
	s_addc_u32 s13, s97, 0
	v_readlane_b32 s10, v253, 22
	s_nop 0
	s_and_b32 s10, s10, 7
	s_add_i32 s10, s10, 1
	s_lshl_b32 s10, s10, 8
	s_add_u32 s12, s12, s10
	s_addc_u32 s13, s13, 0
	v_mov_b32_e32 v0, 0
	buffer_inv sc1
	global_load_dword v0, v0, s[12:13] sc1
	s_waitcnt vmcnt(0)
	v_cmp_eq_u32_e32 vcc, v0, v1
	s_and_saveexec_b64 s[8:9], vcc
	s_cbranch_execz .LBB0_101
	s_add_u32 s10, s96, 0x180200
	s_addc_u32 s11, s97, 0
	s_mov_b32 s24, 1
	s_mov_b64 s[14:15], 0
	v_mov_b32_e32 v0, 0
	s_branch .LBB0_92

; __device__ __forceinline__ unsigned xb_add(unsigned* p, unsigned v) { return __hip_atomic_fetch_add(p, v, __ATOMIC_RELAXED, __HIP_MEMORY_SCOPE_AGENT); }
; __device__ __forceinline__ void xcd_barrier(const XcdBarrier& b) {
;     ...
;             if (og + 1u == (tg + 1u) * nx) xb_add(&bar[XB_TOPGEN], 1u);
.LBB0_117:
	s_or_b64 exec, exec, s[6:7]
	s_and_saveexec_b64 s[6:7], s[10:11]
	s_cbranch_execz .LBB0_119
	v_mov_b32_e32 v2, 1
	global_atomic_add v[0:1], v2, off
	v_mov_b32_e32 v3, 0
	global_atomic_add v3, v2, s[8:9] offset:256
	global_atomic_add v3, v2, s[8:9] offset:512
	global_atomic_add v3, v2, s[8:9] offset:768
	global_atomic_add v3, v2, s[8:9] offset:1024
	global_atomic_add v3, v2, s[8:9] offset:1280
	global_atomic_add v3, v2, s[8:9] offset:1536
	global_atomic_add v3, v2, s[8:9] offset:1792
	global_atomic_add v3, v2, s[8:9] offset:2048

; __device__ __forceinline__ unsigned xb_ld(unsigned* p)              { return __hip_atomic_load(p, __ATOMIC_RELAXED, __HIP_MEMORY_SCOPE_AGENT); }
; #define XB_SPIN(cond, bar) do { unsigned _sp = 0; while (cond) { __builtin_amdgcn_s_sleep(1); \
;     if ((++_sp & 255u) == 0u) { if (xb_ld(&(bar)[XB_TMO])) break; if (_sp > XB_SPIN_CAP) { atomicAdd(&(bar)[XB_TMO], 1u); break; } } } } while (0)
; __device__ __forceinline__ void xcd_barrier(const XcdBarrier& b) {
;     ...
;         } else {
;             XB_SPIN(xb_ld(&bar[XB_XGEN(b.x)]) == gen, bar);
;             __builtin_amdgcn_fence(__ATOMIC_ACQUIRE, "agent");
;             asm volatile("s_waitcnt vmcnt(0)" ::: "memory");
;         }
.LBB0_191:
	s_or_b64 exec, exec, s[6:7]
	v_cvt_f32_u32_e32 v4, v2
	s_waitcnt vmcnt(0)
	v_readfirstlane_b32 s4, v3
	v_sub_u32_e32 v3, 0, v2
	v_rcp_iflag_f32_e32 v4, v4
	v_add_u32_e32 v5, s4, v1
	v_mul_f32_e32 v4, 0x4f7ffffe, v4
	v_cvt_u32_f32_e32 v4, v4
	v_mul_lo_u32 v1, v3, v4
	v_mul_hi_u32 v1, v4, v1
	v_add_u32_e32 v1, v4, v1
	v_mul_hi_u32 v1, v5, v1
	v_mul_lo_u32 v3, v1, v2
	v_sub_u32_e32 v3, v5, v3
	v_add_u32_e32 v4, 1, v1
	v_cmp_ge_u32_e32 vcc, v3, v2
	s_nop 1
	v_cndmask_b32_e32 v1, v1, v4, vcc
	v_sub_u32_e32 v4, v3, v2
	v_cndmask_b32_e32 v3, v3, v4, vcc
	v_add_u32_e32 v4, 1, v1
	v_cmp_ge_u32_e32 vcc, v3, v2
	v_add_u32_e32 v3, 1, v5
	s_nop 0
	v_cndmask_b32_e32 v1, v1, v4, vcc
	v_mul_lo_u32 v4, v2, v1
	v_add_u32_e32 v2, v4, v2
	v_cmp_ne_u32_e32 vcc, v3, v2
	s_and_saveexec_b64 s[4:5], vcc
	s_xor_b64 s[4:5], exec, s[4:5]
	s_cbranch_execz .LBB0_205
	s_waitcnt lgkmcnt(0)
	s_add_u32 s10, s96, 0x183500
	s_addc_u32 s11, s97, 0
	v_readlane_b32 s12, v253, 22
	s_nop 0
	s_and_b32 s12, s12, 7
	s_add_i32 s12, s12, 1
	s_lshl_b32 s12, s12, 8
	s_add_u32 s10, s10, s12
	s_addc_u32 s11, s11, 0
	v_mov_b32_e32 v0, 0
	buffer_inv sc1
	global_load_dword v0, v0, s[10:11] sc1
	s_waitcnt vmcnt(0)
	v_cmp_eq_u32_e32 vcc, v0, v1
	s_and_saveexec_b64 s[6:7], vcc
	s_cbranch_execz .LBB0_204
	s_add_u32 s8, s96, 0x180200
	s_addc_u32 s9, s97, 0
	s_mov_b32 s22, 1
	s_mov_b64 s[12:13], 0
	v_mov_b32_e32 v0, 0
	s_branch .LBB0_195

; __device__ __forceinline__ unsigned xb_add(unsigned* p, unsigned v) { return __hip_atomic_fetch_add(p, v, __ATOMIC_RELAXED, __HIP_MEMORY_SCOPE_AGENT); }
; __device__ __forceinline__ void xcd_barrier(const XcdBarrier& b) {
;     ...
;             if (og + 1u == (tg + 1u) * nx) xb_add(&bar[XB_TOPGEN], 1u);
.LBB0_220:
	s_or_b64 exec, exec, s[4:5]
	s_and_saveexec_b64 s[4:5], s[8:9]
	s_cbranch_execz .LBB0_222
	v_mov_b32_e32 v2, 1
	global_atomic_add v[0:1], v2, off
	v_mov_b32_e32 v3, 0
	global_atomic_add v3, v2, s[6:7] offset:256
	global_atomic_add v3, v2, s[6:7] offset:512
	global_atomic_add v3, v2, s[6:7] offset:768
	global_atomic_add v3, v2, s[6:7] offset:1024
	global_atomic_add v3, v2, s[6:7] offset:1280
	global_atomic_add v3, v2, s[6:7] offset:1536
	global_atomic_add v3, v2, s[6:7] offset:1792
	global_atomic_add v3, v2, s[6:7] offset:2048

; __device__ __forceinline__ unsigned xb_ld(unsigned* p)              { return __hip_atomic_load(p, __ATOMIC_RELAXED, __HIP_MEMORY_SCOPE_AGENT); }
; #define XB_SPIN(cond, bar) do { unsigned _sp = 0; while (cond) { __builtin_amdgcn_s_sleep(1); \
;     if ((++_sp & 255u) == 0u) { if (xb_ld(&(bar)[XB_TMO])) break; if (_sp > XB_SPIN_CAP) { atomicAdd(&(bar)[XB_TMO], 1u); break; } } } } while (0)
; __device__ __forceinline__ void xcd_barrier(const XcdBarrier& b) {
;     ...
;         } else {
;             XB_SPIN(xb_ld(&bar[XB_XGEN(b.x)]) == gen, bar);
;             __builtin_amdgcn_fence(__ATOMIC_ACQUIRE, "agent");
;             asm volatile("s_waitcnt vmcnt(0)" ::: "memory");
;         }
.LBB0_458:
	s_or_b64 exec, exec, s[6:7]
	v_cvt_f32_u32_e32 v4, v2
	s_waitcnt vmcnt(0)
	v_readfirstlane_b32 s4, v3
	v_sub_u32_e32 v3, 0, v2
	v_rcp_iflag_f32_e32 v4, v4
	v_add_u32_e32 v5, s4, v1
	v_mul_f32_e32 v4, 0x4f7ffffe, v4
	v_cvt_u32_f32_e32 v4, v4
	v_mul_lo_u32 v1, v3, v4
	v_mul_hi_u32 v1, v4, v1
	v_add_u32_e32 v1, v4, v1
	v_mul_hi_u32 v1, v5, v1
	v_mul_lo_u32 v3, v1, v2
	v_sub_u32_e32 v3, v5, v3
	v_add_u32_e32 v4, 1, v1
	v_cmp_ge_u32_e32 vcc, v3, v2
	s_nop 1
	v_cndmask_b32_e32 v1, v1, v4, vcc
	v_sub_u32_e32 v4, v3, v2
	v_cndmask_b32_e32 v3, v3, v4, vcc
	v_add_u32_e32 v4, 1, v1
	v_cmp_ge_u32_e32 vcc, v3, v2
	v_add_u32_e32 v3, 1, v5
	s_nop 0
	v_cndmask_b32_e32 v1, v1, v4, vcc
	v_mul_lo_u32 v4, v2, v1
	v_add_u32_e32 v2, v4, v2
	v_cmp_ne_u32_e32 vcc, v3, v2
	s_and_saveexec_b64 s[4:5], vcc
	s_xor_b64 s[4:5], exec, s[4:5]
	s_cbranch_execz .LBB0_472
	s_waitcnt lgkmcnt(0)
	s_add_u32 s12, s96, 0x183500
	s_addc_u32 s13, s97, 0
	v_readlane_b32 s10, v253, 22
	s_nop 0
	s_and_b32 s10, s10, 7
	s_add_i32 s10, s10, 1
	s_lshl_b32 s10, s10, 8
	s_add_u32 s12, s12, s10
	s_addc_u32 s13, s13, 0
	v_mov_b32_e32 v0, 0
	buffer_inv sc1
	global_load_dword v0, v0, s[12:13] sc1
	s_waitcnt vmcnt(0)
	v_cmp_eq_u32_e32 vcc, v0, v1
	s_and_saveexec_b64 s[6:7], vcc
	s_cbranch_execz .LBB0_471
	s_add_u32 s8, s96, 0x180200
	s_addc_u32 s9, s97, 0
	s_mov_b32 s24, 1
	s_mov_b64 s[14:15], 0
	v_mov_b32_e32 v0, 0
	s_branch .LBB0_462
